# phase 0 f32-to-bf16 row copies: eight loads per row issued up front with counted waits (was load, vmcnt(0), convert, store x8); LN prompt rows touch all row segments first
# speedup vs baseline: 1.0174x; 1.0099x over previous
.LBB0_155:
	v_lshl_add_u64 v[2:3], s[66:67], 0, v[36:37]
	s_mov_b64 s[0:1], 0x2600000
	v_lshl_add_u64 v[10:11], v[2:3], 0, s[0:1]
	v_add_co_u32_e32 v2, vcc, 0x2600000, v2
	s_mov_b64 s[0:1], 0xe00
	s_nop 0
	v_addc_co_u32_e32 v3, vcc, 0, v3, vcc
	global_load_dwordx2 v[222:223], v[10:11], off
	global_load_dwordx2 v[222:223], v[10:11], off offset:512
	global_load_dwordx2 v[222:223], v[10:11], off offset:1024
	global_load_dwordx2 v[222:223], v[10:11], off offset:1536
	global_load_dwordx2 v[222:223], v[10:11], off offset:2048
	global_load_dwordx2 v[222:223], v[10:11], off offset:2560
	global_load_dwordx2 v[222:223], v[10:11], off offset:3072
	global_load_dwordx2 v[222:223], v[10:11], off offset:3584
	v_lshl_add_u64 v[220:221], v[10:11], 0, s[70:71]
	global_load_dwordx2 v[222:223], v[220:221], off
	global_load_dwordx2 v[222:223], v[220:221], off offset:512
	global_load_dwordx2 v[222:223], v[220:221], off offset:1024
	global_load_dwordx2 v[222:223], v[220:221], off offset:1536
	global_load_dwordx2 v[222:223], v[220:221], off offset:2048
	global_load_dwordx2 v[222:223], v[220:221], off offset:2560
	global_load_dwordx2 v[222:223], v[220:221], off offset:3072
	global_load_dwordx2 v[222:223], v[220:221], off offset:3584
	v_lshl_add_u64 v[220:221], v[220:221], 0, s[70:71]
	global_load_dwordx2 v[222:223], v[220:221], off
	global_load_dwordx2 v[222:223], v[220:221], off offset:512
	global_load_dwordx2 v[222:223], v[220:221], off offset:1024
	global_load_dwordx2 v[222:223], v[220:221], off offset:1536
	global_load_dwordx2 v[222:223], v[220:221], off offset:2048
	global_load_dwordx2 v[222:223], v[220:221], off offset:2560
	global_load_dwordx2 v[222:223], v[220:221], off offset:3072
	global_load_dwordx2 v[222:223], v[220:221], off offset:3584
	v_lshl_add_u64 v[220:221], v[220:221], 0, s[70:71]
	global_load_dwordx2 v[222:223], v[220:221], off
	global_load_dwordx2 v[222:223], v[220:221], off offset:512
	global_load_dwordx2 v[222:223], v[220:221], off offset:1024
	global_load_dwordx2 v[222:223], v[220:221], off offset:1536
	global_load_dwordx2 v[222:223], v[220:221], off offset:2048
	global_load_dwordx2 v[222:223], v[220:221], off offset:2560
	global_load_dwordx2 v[222:223], v[220:221], off offset:3072
	global_load_dwordx2 v[222:223], v[220:221], off offset:3584
	global_load_dwordx2 v[4:5], v[2:3], off
	global_load_dwordx2 v[6:7], v[10:11], off offset:512
	s_nop 0
	global_load_dwordx2 v[2:3], v[10:11], off offset:1024
	global_load_dwordx2 v[8:9], v[10:11], off offset:1536
	s_andn2_b64 vcc, exec, s[22:23]
	s_waitcnt vmcnt(0)
	v_lshlrev_b32_e32 v116, 16, v4
	v_lshlrev_b32_e32 v117, 16, v6
	v_and_b32_e32 v179, 0xffff0000, v6
	v_lshlrev_b32_e32 v112, 16, v8
	v_and_b32_e32 v113, 0xffff0000, v8
	v_lshlrev_b32_e32 v110, 16, v9
	v_and_b32_e32 v111, 0xffff0000, v9
	global_load_dwordx2 v[8:9], v[10:11], off offset:2048
	v_and_b32_e32 v178, 0xffff0000, v4
	v_lshlrev_b32_e32 v162, 16, v5
	v_lshlrev_b32_e32 v163, 16, v7
	v_and_b32_e32 v181, 0xffff0000, v7
	v_and_b32_e32 v180, 0xffff0000, v5
	v_pk_add_f32 v[4:5], v[116:117], v[178:179]
	v_pk_add_f32 v[6:7], v[162:163], v[180:181]
	v_lshlrev_b32_e32 v157, 16, v3
	v_lshlrev_b32_e32 v156, 16, v2
	v_and_b32_e32 v147, 0xffff0000, v3
	v_and_b32_e32 v146, 0xffff0000, v2
	v_pk_add_f32 v[4:5], v[4:5], v[6:7]
	v_pk_add_f32 v[2:3], v[156:157], v[146:147]
	v_add_f32_e32 v0, 0, v4
	v_pk_add_f32 v[2:3], v[2:3], v[2:3] op_sel:[0,1] op_sel_hi:[1,0]
	v_add_f32_e32 v88, v0, v5
	v_add_f32_e32 v86, v112, v113
	v_add_f32_e32 v84, v110, v111
	s_waitcnt vmcnt(0)
	v_lshlrev_b32_e32 v89, 16, v8
	v_and_b32_e32 v83, 0xffff0000, v8
	v_lshlrev_b32_e32 v87, 16, v9
	v_and_b32_e32 v85, 0xffff0000, v9
	global_load_dwordx2 v[8:9], v[10:11], off offset:2560
	global_load_dwordx2 v[12:13], v[10:11], off offset:3072
	v_mov_b32_e32 v3, v83
	v_pk_add_f32 v[2:3], v[88:89], v[2:3]
	v_pk_add_f32 v[4:5], v[86:87], v[84:85]
	s_waitcnt vmcnt(1)
	v_lshlrev_b32_e32 v141, 16, v9
	s_waitcnt vmcnt(0)
	v_lshlrev_b32_e32 v58, 16, v12
	v_and_b32_e32 v59, 0xffff0000, v12
	v_lshlrev_b32_e32 v60, 16, v13
	v_and_b32_e32 v61, 0xffff0000, v13
	v_lshl_add_u64 v[12:13], v[10:11], 0, s[0:1]
	global_load_dwordx2 v[10:11], v[10:11], off offset:3584
	v_lshl_add_u64 v[38:39], v[12:13], 0, s[82:83]
	v_lshl_add_u64 v[50:51], v[38:39], 0, s[0:1]
	v_lshl_add_u64 v[50:51], v[50:51], 0, s[82:83]
	v_lshl_add_u64 v[68:69], v[50:51], 0, s[0:1]
	v_lshl_add_u64 v[70:71], v[68:69], 0, s[82:83]
	v_lshlrev_b32_e32 v140, 16, v8
	v_and_b32_e32 v143, 0xffff0000, v9
	v_and_b32_e32 v142, 0xffff0000, v8
	v_pk_add_f32 v[2:3], v[2:3], v[4:5]
	v_pk_add_f32 v[4:5], v[140:141], v[142:143]
	v_pk_add_f32 v[2:3], v[2:3], v[2:3] op_sel:[0,1] op_sel_hi:[1,0]
	v_pk_add_f32 v[4:5], v[4:5], v[4:5] op_sel:[0,1] op_sel_hi:[1,0]
	v_add_f32_e32 v46, v58, v59
	v_add_f32_e32 v44, v60, v61
	s_waitcnt vmcnt(0)
	v_lshlrev_b32_e32 v42, 16, v10
	v_and_b32_e32 v43, 0xffff0000, v10
	v_lshlrev_b32_e32 v47, 16, v11
	v_and_b32_e32 v45, 0xffff0000, v11
	global_load_dwordx2 v[12:13], v[38:39], off
	global_load_dwordx2 v[124:125], v[38:39], off offset:512
	global_load_dwordx2 v[10:11], v[38:39], off offset:1024
	global_load_dwordx2 v[40:41], v[38:39], off offset:1536
	v_mov_b32_e32 v3, v42
	v_mov_b32_e32 v5, v43
	v_pk_add_f32 v[2:3], v[2:3], v[4:5]
	v_pk_add_f32 v[4:5], v[46:47], v[44:45]
	s_waitcnt vmcnt(3)
	v_lshlrev_b32_e32 v200, 16, v12
	v_pk_add_f32 v[2:3], v[2:3], v[4:5]
	s_waitcnt vmcnt(2)
	v_lshlrev_b32_e32 v201, 16, v124
	s_waitcnt vmcnt(0)
	v_lshlrev_b32_e32 v118, 16, v40
	v_and_b32_e32 v119, 0xffff0000, v40
	v_lshlrev_b32_e32 v114, 16, v41
	v_and_b32_e32 v115, 0xffff0000, v41
	global_load_dwordx2 v[40:41], v[38:39], off offset:2048
	v_add_f32_e32 v0, v2, v3
	v_and_b32_e32 v189, 0xffff0000, v124
	v_and_b32_e32 v188, 0xffff0000, v12
	v_add_f32_dpp v0, v0, v0 quad_perm:[1,0,3,2] row_mask:0xf bank_mask:0xf bound_ctrl:1
	v_lshlrev_b32_e32 v151, 16, v125
	v_lshlrev_b32_e32 v150, 16, v13
	v_add_f32_dpp v0, v0, v0 quad_perm:[2,3,0,1] row_mask:0xf bank_mask:0xf bound_ctrl:1
	v_and_b32_e32 v177, 0xffff0000, v125
	v_and_b32_e32 v176, 0xffff0000, v13
	v_add_f32_dpp v0, v0, v0 row_half_mirror row_mask:0xf bank_mask:0xf bound_ctrl:1
	v_pk_add_f32 v[4:5], v[150:151], v[176:177]
	v_lshlrev_b32_e32 v155, 16, v11
	v_add_f32_dpp v0, v0, v0 row_ror:8 row_mask:0xf bank_mask:0xf bound_ctrl:1
	v_lshlrev_b32_e32 v154, 16, v10
	v_readlane_b32 s2, v0, 16
	v_readlane_b32 s3, v0, 48
	v_readlane_b32 s0, v0, 0
	v_readlane_b32 s1, v0, 32
	v_mov_b32_e32 v2, s2
	v_mov_b32_e32 v3, s3
	v_pk_add_f32 v[2:3], s[0:1], v[2:3]
	v_and_b32_e32 v153, 0xffff0000, v11
	v_add_f32_e32 v0, v2, v3
	v_pk_add_f32 v[2:3], v[200:201], v[188:189]
	v_and_b32_e32 v152, 0xffff0000, v10
	v_pk_add_f32 v[2:3], v[2:3], v[4:5]
	v_add_f32_e32 v80, v118, v119
	v_add_f32_e32 v2, 0, v2
	v_add_f32_e32 v104, v2, v3
	v_pk_add_f32 v[2:3], v[154:155], v[152:153]
	v_add_f32_e32 v78, v114, v115
	v_pk_add_f32 v[2:3], v[2:3], v[2:3] op_sel:[0,1] op_sel_hi:[1,0]
	v_fmac_f32_e32 v146, 0xba000000, v0
	v_fmac_f32_e32 v156, 0xba000000, v0
	v_fmac_f32_e32 v147, 0xba000000, v0
	v_fmac_f32_e32 v157, 0xba000000, v0
	v_mov_b32_e32 v6, v156
	v_mov_b32_e32 v7, v146
	v_pk_mul_f32 v[6:7], v[6:7], v[6:7]
	v_mov_b32_e32 v8, v157
	v_mov_b32_e32 v9, v147
	v_fmac_f32_e32 v113, 0xba000000, v0
	v_fmac_f32_e32 v112, 0xba000000, v0
	v_pk_fma_f32 v[6:7], v[8:9], v[8:9], v[6:7]
	v_fmac_f32_e32 v111, 0xba000000, v0
	v_fmac_f32_e32 v110, 0xba000000, v0
	v_pk_mul_f32 v[8:9], v[112:113], v[112:113]
	v_fmac_f32_e32 v178, 0xba000000, v0
	v_fmac_f32_e32 v116, 0xba000000, v0
	v_fmac_f32_e32 v117, 0xba000000, v0
	v_pk_fma_f32 v[8:9], v[110:111], v[110:111], v[8:9]
	v_fmac_f32_e32 v180, 0xba000000, v0
	v_fmac_f32_e32 v162, 0xba000000, v0
	v_mov_b32_e32 v10, v116
	v_mov_b32_e32 v11, v178
	v_fmac_f32_e32 v163, 0xba000000, v0
	v_fmac_f32_e32 v179, 0xba000000, v0
	v_mov_b32_e32 v178, v117
	v_fmac_f32_e32 v89, 0xba000000, v0
	v_fmac_f32_e32 v142, 0xba000000, v0
	v_fmac_f32_e32 v140, 0xba000000, v0
	v_mov_b32_e32 v12, v162
	v_mov_b32_e32 v13, v180
	v_fmac_f32_e32 v181, 0xba000000, v0
	v_mov_b32_e32 v180, v163
	v_fmac_f32_e32 v87, 0xba000000, v0
	v_fmac_f32_e32 v83, 0xba000000, v0
	v_mov_b32_e32 v82, v89
	v_fmac_f32_e32 v143, 0xba000000, v0
	v_fmac_f32_e32 v141, 0xba000000, v0
	v_fmac_f32_e32 v85, 0xba000000, v0
	v_mov_b32_e32 v84, v87
	v_fmac_f32_e32 v61, 0xba000000, v0
	v_fmac_f32_e32 v60, 0xba000000, v0
	v_fmac_f32_e32 v59, 0xba000000, v0
	v_fmac_f32_e32 v58, 0xba000000, v0
	v_fmac_f32_e32 v45, 0xba000000, v0
	v_fmac_f32_e32 v47, 0xba000000, v0
	v_fmac_f32_e32 v43, 0xba000000, v0
	s_waitcnt vmcnt(0)
	v_lshlrev_b32_e32 v105, 16, v40
	v_and_b32_e32 v91, 0xffff0000, v40
	v_lshlrev_b32_e32 v81, 16, v41
	v_and_b32_e32 v79, 0xffff0000, v41
	global_load_dwordx2 v[130:131], v[38:39], off offset:2560
	global_load_dwordx2 v[40:41], v[38:39], off offset:3072
	v_mov_b32_e32 v3, v91
	global_load_dwordx2 v[38:39], v[38:39], off offset:3584
	s_nop 0
	global_load_dwordx2 v[134:135], v[50:51], off
	global_load_dwordx2 v[136:137], v[50:51], off offset:512
	global_load_dwordx2 v[132:133], v[50:51], off offset:1024
	global_load_dwordx2 v[52:53], v[50:51], off offset:1536
	v_pk_add_f32 v[2:3], v[104:105], v[2:3]
	v_pk_add_f32 v[4:5], v[80:81], v[78:79]
	v_fmac_f32_e32 v42, 0xba000000, v0
	v_pk_add_f32 v[2:3], v[2:3], v[4:5]
	v_mov_b32_e32 v44, v47
	v_pk_add_f32 v[2:3], v[2:3], v[2:3] op_sel:[0,1] op_sel_hi:[1,0]
	s_waitcnt vmcnt(6)
	v_lshlrev_b32_e32 v127, 16, v131
	v_lshlrev_b32_e32 v126, 16, v130
	v_and_b32_e32 v125, 0xffff0000, v131
	v_and_b32_e32 v124, 0xffff0000, v130
	s_waitcnt vmcnt(0)
	v_lshlrev_b32_e32 v120, 16, v52
	v_and_b32_e32 v121, 0xffff0000, v52
	v_lshlrev_b32_e32 v122, 16, v53
	v_and_b32_e32 v123, 0xffff0000, v53
	global_load_dwordx2 v[52:53], v[50:51], off offset:2048
	v_pk_add_f32 v[4:5], v[126:127], v[124:125]
	v_lshlrev_b32_e32 v62, 16, v40
	v_and_b32_e32 v63, 0xffff0000, v40
	v_lshlrev_b32_e32 v56, 16, v41
	v_and_b32_e32 v57, 0xffff0000, v41
	v_lshlrev_b32_e32 v48, 16, v38
	v_and_b32_e32 v49, 0xffff0000, v38
	v_pk_add_f32 v[4:5], v[4:5], v[4:5] op_sel:[0,1] op_sel_hi:[1,0]
	v_lshlrev_b32_e32 v41, 16, v39
	v_and_b32_e32 v39, 0xffff0000, v39
	v_add_f32_e32 v40, v62, v63
	v_add_f32_e32 v38, v56, v57
	v_mov_b32_e32 v3, v48
	v_mov_b32_e32 v5, v49
	v_pk_add_f32 v[2:3], v[2:3], v[4:5]
	v_pk_add_f32 v[4:5], v[40:41], v[38:39]
	v_lshlrev_b32_e32 v195, 16, v136
	v_pk_add_f32 v[2:3], v[2:3], v[4:5]
	v_lshlrev_b32_e32 v194, 16, v134
	v_add_f32_e32 v2, v2, v3
	v_and_b32_e32 v183, 0xffff0000, v136
	v_and_b32_e32 v182, 0xffff0000, v134
	v_add_f32_dpp v2, v2, v2 quad_perm:[1,0,3,2] row_mask:0xf bank_mask:0xf bound_ctrl:1
	v_lshlrev_b32_e32 v187, 16, v137
	v_lshlrev_b32_e32 v186, 16, v135
	v_add_f32_dpp v2, v2, v2 quad_perm:[2,3,0,1] row_mask:0xf bank_mask:0xf bound_ctrl:1
	v_and_b32_e32 v185, 0xffff0000, v137
	v_and_b32_e32 v184, 0xffff0000, v135
	v_add_f32_dpp v2, v2, v2 row_half_mirror row_mask:0xf bank_mask:0xf bound_ctrl:1
	v_pk_add_f32 v[4:5], v[186:187], v[184:185]
	v_lshlrev_b32_e32 v169, 16, v133
	v_add_f32_dpp v2, v2, v2 row_ror:8 row_mask:0xf bank_mask:0xf bound_ctrl:1
	v_lshlrev_b32_e32 v168, 16, v132
	v_readlane_b32 s2, v2, 16
	v_readlane_b32 s3, v2, 48
	v_readlane_b32 s0, v2, 0
	v_readlane_b32 s1, v2, 32
	v_mov_b32_e32 v2, s2
	v_mov_b32_e32 v3, s3
	v_pk_add_f32 v[2:3], s[0:1], v[2:3]
	v_and_b32_e32 v167, 0xffff0000, v133
	v_add_f32_e32 v38, v2, v3
	v_pk_add_f32 v[2:3], v[194:195], v[182:183]
	v_and_b32_e32 v166, 0xffff0000, v132
	v_pk_add_f32 v[2:3], v[2:3], v[4:5]
	v_add_f32_e32 v96, v120, v121
	v_add_f32_e32 v2, 0, v2
	v_add_f32_e32 v98, v2, v3
	v_pk_add_f32 v[2:3], v[168:169], v[166:167]
	v_add_f32_e32 v94, v122, v123
	v_pk_add_f32 v[2:3], v[2:3], v[2:3] op_sel:[0,1] op_sel_hi:[1,0]
	v_fmac_f32_e32 v188, 0xba000000, v38
	v_fmac_f32_e32 v200, 0xba000000, v38
	v_fmac_f32_e32 v189, 0xba000000, v38
	v_fmac_f32_e32 v201, 0xba000000, v38
	v_fmac_f32_e32 v176, 0xba000000, v38
	v_fmac_f32_e32 v150, 0xba000000, v38
	v_fmac_f32_e32 v151, 0xba000000, v38
	v_fmac_f32_e32 v152, 0xba000000, v38
	v_fmac_f32_e32 v154, 0xba000000, v38
	v_fmac_f32_e32 v177, 0xba000000, v38
	v_fmac_f32_e32 v153, 0xba000000, v38
	v_fmac_f32_e32 v155, 0xba000000, v38
	v_fmac_f32_e32 v119, 0xba000000, v38
	v_fmac_f32_e32 v118, 0xba000000, v38
	v_fmac_f32_e32 v105, 0xba000000, v38
	v_fmac_f32_e32 v115, 0xba000000, v38
	v_fmac_f32_e32 v114, 0xba000000, v38
	v_fmac_f32_e32 v81, 0xba000000, v38
	v_fmac_f32_e32 v91, 0xba000000, v38
	v_mov_b32_e32 v90, v105
	v_fmac_f32_e32 v124, 0xba000000, v38
	v_fmac_f32_e32 v126, 0xba000000, v38
	v_fmac_f32_e32 v79, 0xba000000, v38
	v_mov_b32_e32 v78, v81
	v_fmac_f32_e32 v125, 0xba000000, v38
	v_fmac_f32_e32 v127, 0xba000000, v38
	v_fmac_f32_e32 v63, 0xba000000, v38
	v_fmac_f32_e32 v62, 0xba000000, v38
	s_waitcnt vmcnt(0)
	v_lshlrev_b32_e32 v99, 16, v52
	v_and_b32_e32 v93, 0xffff0000, v52
	v_lshlrev_b32_e32 v97, 16, v53
	v_and_b32_e32 v95, 0xffff0000, v53
	global_load_dwordx2 v[148:149], v[50:51], off offset:2560
	global_load_dwordx2 v[52:53], v[50:51], off offset:3072
	v_mov_b32_e32 v3, v93
	v_pk_add_f32 v[2:3], v[98:99], v[2:3]
	v_pk_add_f32 v[4:5], v[96:97], v[94:95]
	v_fmac_f32_e32 v57, 0xba000000, v38
	v_pk_add_f32 v[2:3], v[2:3], v[4:5]
	v_fmac_f32_e32 v56, 0xba000000, v38
	v_pk_add_f32 v[2:3], v[2:3], v[2:3] op_sel:[0,1] op_sel_hi:[1,0]
	v_fmac_f32_e32 v41, 0xba000000, v38
	v_fmac_f32_e32 v49, 0xba000000, v38
	v_fmac_f32_e32 v48, 0xba000000, v38
	v_fmac_f32_e32 v39, 0xba000000, v38
	v_mov_b32_e32 v38, v41
	s_waitcnt vmcnt(1)
	v_lshlrev_b32_e32 v137, 16, v149
	s_waitcnt vmcnt(0)
	v_lshlrev_b32_e32 v64, 16, v52
	v_and_b32_e32 v65, 0xffff0000, v52
	v_lshlrev_b32_e32 v66, 16, v53
	v_and_b32_e32 v67, 0xffff0000, v53
	global_load_dwordx2 v[52:53], v[50:51], off offset:3584
	global_load_dwordx2 v[160:161], v[70:71], off
	global_load_dwordx2 v[164:165], v[70:71], off offset:512
	global_load_dwordx2 v[158:159], v[70:71], off offset:1024
	global_load_dwordx2 v[68:69], v[70:71], off offset:1536
	v_lshlrev_b32_e32 v136, 16, v148
	v_and_b32_e32 v135, 0xffff0000, v149
	v_and_b32_e32 v134, 0xffff0000, v148
	v_pk_add_f32 v[4:5], v[136:137], v[134:135]
	v_add_f32_e32 v54, v64, v65
	v_pk_add_f32 v[4:5], v[4:5], v[4:5] op_sel:[0,1] op_sel_hi:[1,0]
	v_mov_b32_e32 v148, v8
	v_mov_b32_e32 v149, v6
	v_mov_b32_e32 v6, v9
	v_pk_add_f32 v[6:7], v[148:149], v[6:7]
	v_mov_b32_e32 v148, v140
	v_mov_b32_e32 v149, v142
	v_pk_mul_f32 v[8:9], v[82:83], v[82:83]
	v_pk_mul_f32 v[148:149], v[148:149], v[148:149]
	v_pk_fma_f32 v[8:9], v[84:85], v[84:85], v[8:9]
	s_waitcnt vmcnt(3)
	v_lshlrev_b32_e32 v198, 16, v160
	s_waitcnt vmcnt(2)
	v_lshlrev_b32_e32 v199, 16, v164
	v_lshlrev_b32_e32 v50, 16, v52
	s_waitcnt vmcnt(0)
	v_lshlrev_b32_e32 v144, 16, v68
	v_and_b32_e32 v145, 0xffff0000, v68
	v_lshlrev_b32_e32 v128, 16, v69
	v_and_b32_e32 v129, 0xffff0000, v69
	global_load_dwordx2 v[68:69], v[70:71], off offset:2048
	v_and_b32_e32 v51, 0xffff0000, v52
	v_lshlrev_b32_e32 v55, 16, v53
	v_and_b32_e32 v53, 0xffff0000, v53
	v_add_f32_e32 v52, v66, v67
	v_mov_b32_e32 v3, v50
	v_mov_b32_e32 v5, v51
	v_pk_add_f32 v[2:3], v[2:3], v[4:5]
	v_pk_add_f32 v[4:5], v[54:55], v[52:53]
	v_and_b32_e32 v197, 0xffff0000, v164
	v_pk_add_f32 v[2:3], v[2:3], v[4:5]
	v_and_b32_e32 v196, 0xffff0000, v160
	v_add_f32_e32 v2, v2, v3
	v_lshlrev_b32_e32 v193, 16, v165
	v_lshlrev_b32_e32 v192, 16, v161
	v_add_f32_dpp v2, v2, v2 quad_perm:[1,0,3,2] row_mask:0xf bank_mask:0xf bound_ctrl:1
	v_and_b32_e32 v191, 0xffff0000, v165
	v_and_b32_e32 v190, 0xffff0000, v161
	v_add_f32_dpp v2, v2, v2 quad_perm:[2,3,0,1] row_mask:0xf bank_mask:0xf bound_ctrl:1
	v_pk_add_f32 v[4:5], v[192:193], v[190:191]
	v_lshlrev_b32_e32 v173, 16, v159
	v_add_f32_dpp v2, v2, v2 row_half_mirror row_mask:0xf bank_mask:0xf bound_ctrl:1
	v_lshlrev_b32_e32 v172, 16, v158
	v_and_b32_e32 v171, 0xffff0000, v159
	v_add_f32_dpp v2, v2, v2 row_ror:8 row_mask:0xf bank_mask:0xf bound_ctrl:1
	v_and_b32_e32 v170, 0xffff0000, v158
	v_readlane_b32 s2, v2, 16
	v_readlane_b32 s3, v2, 48
	v_readlane_b32 s0, v2, 0
	v_readlane_b32 s1, v2, 32
	v_mov_b32_e32 v2, s2
	v_mov_b32_e32 v3, s3
	v_pk_add_f32 v[2:3], s[0:1], v[2:3]
	v_add_f32_e32 v102, v144, v145
	v_add_f32_e32 v40, v2, v3
	v_pk_add_f32 v[2:3], v[198:199], v[196:197]
	v_add_f32_e32 v100, v128, v129
	v_pk_add_f32 v[2:3], v[2:3], v[4:5]
	v_mov_b32_e32 v158, v141
	v_add_f32_e32 v2, 0, v2
	v_add_f32_e32 v108, v2, v3
	v_pk_add_f32 v[2:3], v[172:173], v[170:171]
	v_mov_b32_e32 v159, v143
	v_pk_add_f32 v[2:3], v[2:3], v[2:3] op_sel:[0,1] op_sel_hi:[1,0]
	v_pk_fma_f32 v[148:149], v[158:159], v[158:159], v[148:149]
	v_mov_b32_e32 v159, v8
	v_mov_b32_e32 v158, v148
	v_mov_b32_e32 v8, v149
	v_pk_add_f32 v[8:9], v[158:159], v[8:9]
	v_pk_mul_f32 v[148:149], v[58:59], v[58:59]
	v_pk_mul_f32 v[158:159], v[42:43], v[42:43]
	v_pk_fma_f32 v[148:149], v[60:61], v[60:61], v[148:149]
	v_pk_fma_f32 v[158:159], v[44:45], v[44:45], v[158:159]
	v_mov_b32_e32 v161, v148
	v_mov_b32_e32 v160, v158
	v_mov_b32_e32 v148, v159
	v_pk_add_f32 v[148:149], v[160:161], v[148:149]
	v_pk_mul_f32 v[158:159], v[90:91], v[90:91]
	v_mov_b32_e32 v160, v126
	v_mov_b32_e32 v161, v124
	v_pk_fma_f32 v[158:159], v[78:79], v[78:79], v[158:159]
	v_pk_mul_f32 v[160:161], v[160:161], v[160:161]
	v_mov_b32_e32 v164, v127
	v_mov_b32_e32 v165, v125
	v_pk_fma_f32 v[160:161], v[164:165], v[164:165], v[160:161]
	v_pk_mul_f32 v[164:165], v[62:63], v[62:63]
	v_fmac_f32_e32 v182, 0xba000000, v40
	v_pk_fma_f32 v[164:165], v[56:57], v[56:57], v[164:165]
	v_fmac_f32_e32 v194, 0xba000000, v40
	v_fmac_f32_e32 v184, 0xba000000, v40
	v_fmac_f32_e32 v186, 0xba000000, v40
	v_fmac_f32_e32 v183, 0xba000000, v40
	v_fmac_f32_e32 v195, 0xba000000, v40
	v_fmac_f32_e32 v185, 0xba000000, v40
	v_fmac_f32_e32 v187, 0xba000000, v40
	v_fmac_f32_e32 v166, 0xba000000, v40
	v_fmac_f32_e32 v168, 0xba000000, v40
	v_fmac_f32_e32 v167, 0xba000000, v40
	v_fmac_f32_e32 v169, 0xba000000, v40
	v_fmac_f32_e32 v121, 0xba000000, v40
	s_waitcnt vmcnt(0)
	v_lshlrev_b32_e32 v109, 16, v68
	v_and_b32_e32 v107, 0xffff0000, v68
	v_lshlrev_b32_e32 v103, 16, v69
	v_and_b32_e32 v101, 0xffff0000, v69
	global_load_dwordx2 v[174:175], v[70:71], off offset:2560
	global_load_dwordx2 v[68:69], v[70:71], off offset:3072
	v_mov_b32_e32 v3, v107
	global_load_dwordx2 v[70:71], v[70:71], off offset:3584
	v_pk_add_f32 v[2:3], v[108:109], v[2:3]
	v_pk_add_f32 v[4:5], v[102:103], v[100:101]
	v_fmac_f32_e32 v120, 0xba000000, v40
	v_pk_add_f32 v[2:3], v[2:3], v[4:5]
	v_fmac_f32_e32 v99, 0xba000000, v40
	v_pk_add_f32 v[2:3], v[2:3], v[2:3] op_sel:[0,1] op_sel_hi:[1,0]
	v_fmac_f32_e32 v123, 0xba000000, v40
	v_fmac_f32_e32 v122, 0xba000000, v40
	v_fmac_f32_e32 v97, 0xba000000, v40
	v_fmac_f32_e32 v93, 0xba000000, v40
	v_mov_b32_e32 v92, v99
	v_fmac_f32_e32 v134, 0xba000000, v40
	v_fmac_f32_e32 v136, 0xba000000, v40
	v_fmac_f32_e32 v95, 0xba000000, v40
	v_mov_b32_e32 v94, v97
	v_fmac_f32_e32 v135, 0xba000000, v40
	v_fmac_f32_e32 v137, 0xba000000, v40
	v_fmac_f32_e32 v65, 0xba000000, v40
	v_fmac_f32_e32 v64, 0xba000000, v40
	v_fmac_f32_e32 v67, 0xba000000, v40
	v_fmac_f32_e32 v66, 0xba000000, v40
	v_fmac_f32_e32 v55, 0xba000000, v40
	v_fmac_f32_e32 v51, 0xba000000, v40
	v_fmac_f32_e32 v50, 0xba000000, v40
	v_fmac_f32_e32 v53, 0xba000000, v40
	v_mov_b32_e32 v52, v55
	s_waitcnt vmcnt(2)
	v_lshlrev_b32_e32 v133, 16, v175
	v_lshlrev_b32_e32 v132, 16, v174
	v_and_b32_e32 v131, 0xffff0000, v175
	v_and_b32_e32 v130, 0xffff0000, v174
	v_pk_add_f32 v[4:5], v[132:133], v[130:131]
	s_waitcnt vmcnt(1)
	v_lshlrev_b32_e32 v74, 16, v68
	v_and_b32_e32 v75, 0xffff0000, v68
	v_lshlrev_b32_e32 v68, 16, v69
	v_and_b32_e32 v69, 0xffff0000, v69
	s_waitcnt vmcnt(0)
	v_lshlrev_b32_e32 v76, 16, v70
	v_and_b32_e32 v77, 0xffff0000, v70
	v_pk_add_f32 v[4:5], v[4:5], v[4:5] op_sel:[0,1] op_sel_hi:[1,0]
	v_lshlrev_b32_e32 v73, 16, v71
	v_and_b32_e32 v71, 0xffff0000, v71
	v_add_f32_e32 v72, v74, v75
	v_add_f32_e32 v70, v68, v69
	v_mov_b32_e32 v3, v76
	v_mov_b32_e32 v5, v77
	v_pk_add_f32 v[2:3], v[2:3], v[4:5]
	v_pk_add_f32 v[4:5], v[72:73], v[70:71]
	v_pk_mul_f32 v[174:175], v[48:49], v[48:49]
	v_pk_add_f32 v[2:3], v[2:3], v[4:5]
	v_pk_mul_f32 v[4:5], v[178:179], v[178:179]
	v_add_f32_e32 v2, v2, v3
	v_pk_fma_f32 v[4:5], v[180:181], v[180:181], v[4:5]
	v_pk_fma_f32 v[174:175], v[38:39], v[38:39], v[174:175]
	v_add_f32_dpp v2, v2, v2 quad_perm:[1,0,3,2] row_mask:0xf bank_mask:0xf bound_ctrl:1
	v_add_f32_e32 v0, v4, v5
	v_mov_b32_e32 v4, v201
	v_add_f32_dpp v2, v2, v2 quad_perm:[2,3,0,1] row_mask:0xf bank_mask:0xf bound_ctrl:1
	v_mov_b32_e32 v5, v189
	v_pk_mul_f32 v[4:5], v[4:5], v[4:5]
	v_add_f32_dpp v2, v2, v2 row_half_mirror row_mask:0xf bank_mask:0xf bound_ctrl:1
	s_nop 1
	v_add_f32_dpp v2, v2, v2 row_ror:8 row_mask:0xf bank_mask:0xf bound_ctrl:1
	s_nop 0
	v_readlane_b32 s2, v2, 16
	v_readlane_b32 s3, v2, 48
	v_readlane_b32 s0, v2, 0
	v_readlane_b32 s1, v2, 32
	v_mov_b32_e32 v2, s2
	v_mov_b32_e32 v3, s3
	v_pk_add_f32 v[2:3], s[0:1], v[2:3]
	s_nop 0
	v_add_f32_e32 v46, v2, v3
	v_pk_mul_f32 v[2:3], v[10:11], v[10:11]
	v_fmac_f32_e32 v196, 0xba000000, v46
	v_pk_fma_f32 v[2:3], v[12:13], v[12:13], v[2:3]
	v_fmac_f32_e32 v198, 0xba000000, v46
	v_add_f32_e32 v2, v2, v3
	v_add_f32_e32 v0, v2, v0
	v_add_f32_e32 v0, v7, v0
	v_add_f32_e32 v0, v6, v0
	v_add_f32_e32 v0, v9, v0
	v_add_f32_e32 v0, v8, v0
	v_add_f32_e32 v0, v149, v0
	v_add_f32_e32 v0, v148, v0
	v_mov_b32_e32 v148, v150
	v_mov_b32_e32 v149, v176
	v_add_f32_dpp v0, v0, v0 quad_perm:[1,0,3,2] row_mask:0xf bank_mask:0xf bound_ctrl:1
	v_mov_b32_e32 v176, v151
	v_mov_b32_e32 v6, v154
	v_add_f32_dpp v0, v0, v0 quad_perm:[2,3,0,1] row_mask:0xf bank_mask:0xf bound_ctrl:1
	v_mov_b32_e32 v7, v152
	v_pk_fma_f32 v[4:5], v[176:177], v[176:177], v[4:5]
	v_add_f32_dpp v0, v0, v0 row_half_mirror row_mask:0xf bank_mask:0xf bound_ctrl:1
	v_pk_mul_f32 v[6:7], v[6:7], v[6:7]
	v_mov_b32_e32 v8, v155
	v_add_f32_dpp v0, v0, v0 row_ror:8 row_mask:0xf bank_mask:0xf bound_ctrl:1
	v_mov_b32_e32 v9, v153
	v_readlane_b32 s2, v0, 16
	v_readlane_b32 s3, v0, 48
	v_readlane_b32 s0, v0, 0
	v_readlane_b32 s1, v0, 32
	v_mov_b32_e32 v2, s2
	v_mov_b32_e32 v3, s3
	v_pk_add_f32 v[2:3], s[0:1], v[2:3]
	v_pk_fma_f32 v[6:7], v[8:9], v[8:9], v[6:7]
	v_add_f32_e32 v0, v2, v3
	v_mov_b32_e32 v2, v200
	v_mov_b32_e32 v3, v188
	v_pk_mul_f32 v[2:3], v[2:3], v[2:3]
	v_fmamk_f32 v0, v0, 0x3a000000, v203
	v_pk_fma_f32 v[2:3], v[148:149], v[148:149], v[2:3]
	v_rsq_f32_e32 v116, v0
	v_pk_mul_f32 v[8:9], v[118:119], v[118:119]
	v_add_f32_e32 v0, v4, v5
	v_add_f32_e32 v2, v2, v3
	v_pk_fma_f32 v[8:9], v[114:115], v[114:115], v[8:9]
	v_add_f32_e32 v0, v2, v0
	v_add_f32_e32 v2, v6, v7
	v_add_f32_e32 v0, v2, v0
	v_add_f32_e32 v2, v8, v9
	v_add_f32_e32 v0, v2, v0
	v_add_f32_e32 v2, v158, v159
	v_add_f32_e32 v0, v2, v0
	v_add_f32_e32 v2, v160, v161
	v_add_f32_e32 v0, v2, v0
	v_add_f32_e32 v2, v164, v165
	v_add_f32_e32 v0, v2, v0
	v_add_f32_e32 v2, v174, v175
	v_add_f32_e32 v0, v2, v0
	v_mov_b32_e32 v2, v194
	v_mov_b32_e32 v3, v182
	v_pk_mul_f32 v[2:3], v[2:3], v[2:3]
	v_mov_b32_e32 v4, v186
	v_mov_b32_e32 v5, v184
	v_add_f32_dpp v0, v0, v0 quad_perm:[1,0,3,2] row_mask:0xf bank_mask:0xf bound_ctrl:1
	v_pk_fma_f32 v[2:3], v[4:5], v[4:5], v[2:3]
	v_mov_b32_e32 v4, v195
	v_mov_b32_e32 v5, v183
	v_add_f32_dpp v0, v0, v0 quad_perm:[2,3,0,1] row_mask:0xf bank_mask:0xf bound_ctrl:1
	v_pk_mul_f32 v[4:5], v[4:5], v[4:5]
	v_mov_b32_e32 v6, v187
	v_mov_b32_e32 v7, v185
	v_add_f32_dpp v0, v0, v0 row_half_mirror row_mask:0xf bank_mask:0xf bound_ctrl:1
	v_pk_fma_f32 v[4:5], v[6:7], v[6:7], v[4:5]
	v_mov_b32_e32 v6, v168
	v_mov_b32_e32 v7, v166
	v_add_f32_dpp v0, v0, v0 row_ror:8 row_mask:0xf bank_mask:0xf bound_ctrl:1
	v_pk_mul_f32 v[6:7], v[6:7], v[6:7]
	v_mov_b32_e32 v8, v169
	v_mov_b32_e32 v9, v167
	v_readlane_b32 s0, v0, 0
	v_readlane_b32 s4, v0, 16
	v_readlane_b32 s1, v0, 32
	v_readlane_b32 s5, v0, 48
	v_pk_fma_f32 v[6:7], v[8:9], v[8:9], v[6:7]
	v_pk_mul_f32 v[8:9], v[120:121], v[120:121]
	v_add_f32_e32 v0, v4, v5
	v_add_f32_e32 v2, v2, v3
	v_pk_fma_f32 v[8:9], v[122:123], v[122:123], v[8:9]
	v_pk_mul_f32 v[158:159], v[92:93], v[92:93]
	v_mov_b32_e32 v160, v136
	v_mov_b32_e32 v161, v134
	v_add_f32_e32 v0, v2, v0
	v_add_f32_e32 v2, v6, v7
	v_pk_fma_f32 v[158:159], v[94:95], v[94:95], v[158:159]
	v_pk_mul_f32 v[160:161], v[160:161], v[160:161]
	v_mov_b32_e32 v164, v137
	v_mov_b32_e32 v165, v135
	v_add_f32_e32 v0, v2, v0
	v_add_f32_e32 v2, v8, v9
	v_pk_fma_f32 v[160:161], v[164:165], v[164:165], v[160:161]
	v_pk_mul_f32 v[164:165], v[64:65], v[64:65]
	v_add_f32_e32 v0, v2, v0
	v_add_f32_e32 v2, v158, v159
	v_pk_fma_f32 v[164:165], v[66:67], v[66:67], v[164:165]
	v_pk_mul_f32 v[174:175], v[50:51], v[50:51]
	v_add_f32_e32 v0, v2, v0
	v_add_f32_e32 v2, v160, v161
	v_pk_fma_f32 v[174:175], v[52:53], v[52:53], v[174:175]
	v_add_f32_e32 v0, v2, v0
	v_add_f32_e32 v2, v164, v165
	v_add_f32_e32 v0, v2, v0
	v_add_f32_e32 v2, v174, v175
	v_add_f32_e32 v0, v2, v0
	v_fmac_f32_e32 v190, 0xba000000, v46
	v_fmac_f32_e32 v192, 0xba000000, v46
	v_mov_b32_e32 v2, v198
	v_mov_b32_e32 v3, v196
	v_pk_mul_f32 v[2:3], v[2:3], v[2:3]
	v_mov_b32_e32 v4, v192
	v_mov_b32_e32 v5, v190
	v_fmac_f32_e32 v197, 0xba000000, v46
	v_fmac_f32_e32 v199, 0xba000000, v46
	v_add_f32_dpp v0, v0, v0 quad_perm:[1,0,3,2] row_mask:0xf bank_mask:0xf bound_ctrl:1
	v_pk_fma_f32 v[2:3], v[4:5], v[4:5], v[2:3]
	v_fmac_f32_e32 v191, 0xba000000, v46
	v_fmac_f32_e32 v193, 0xba000000, v46
	v_mov_b32_e32 v4, v199
	v_mov_b32_e32 v5, v197
	v_add_f32_dpp v0, v0, v0 quad_perm:[2,3,0,1] row_mask:0xf bank_mask:0xf bound_ctrl:1
	v_pk_mul_f32 v[4:5], v[4:5], v[4:5]
	v_mov_b32_e32 v6, v193
	v_mov_b32_e32 v7, v191
	v_fmac_f32_e32 v170, 0xba000000, v46
	v_fmac_f32_e32 v172, 0xba000000, v46
	v_add_f32_dpp v0, v0, v0 row_half_mirror row_mask:0xf bank_mask:0xf bound_ctrl:1
	v_pk_fma_f32 v[4:5], v[6:7], v[6:7], v[4:5]
	v_fmac_f32_e32 v171, 0xba000000, v46
	v_fmac_f32_e32 v173, 0xba000000, v46
	v_mov_b32_e32 v6, v172
	v_mov_b32_e32 v7, v170
	v_add_f32_dpp v0, v0, v0 row_ror:8 row_mask:0xf bank_mask:0xf bound_ctrl:1
	v_pk_mul_f32 v[6:7], v[6:7], v[6:7]
	v_mov_b32_e32 v8, v173
	v_mov_b32_e32 v9, v171
	v_fmac_f32_e32 v145, 0xba000000, v46
	v_fmac_f32_e32 v144, 0xba000000, v46
	v_fmac_f32_e32 v109, 0xba000000, v46
	v_readlane_b32 s18, v0, 0
	v_readlane_b32 s26, v0, 16
	v_readlane_b32 s19, v0, 32
	v_readlane_b32 s27, v0, 48
	v_pk_fma_f32 v[6:7], v[8:9], v[8:9], v[6:7]
	v_fmac_f32_e32 v129, 0xba000000, v46
	v_fmac_f32_e32 v128, 0xba000000, v46
	v_pk_mul_f32 v[8:9], v[144:145], v[144:145]
	v_fmac_f32_e32 v103, 0xba000000, v46
	v_fmac_f32_e32 v107, 0xba000000, v46
	v_mov_b32_e32 v106, v109
	v_fmac_f32_e32 v130, 0xba000000, v46
	v_fmac_f32_e32 v132, 0xba000000, v46
	v_add_f32_e32 v0, v4, v5
	v_add_f32_e32 v2, v2, v3
	v_pk_fma_f32 v[8:9], v[128:129], v[128:129], v[8:9]
	v_fmac_f32_e32 v101, 0xba000000, v46
	v_pk_mul_f32 v[158:159], v[106:107], v[106:107]
	v_mov_b32_e32 v100, v103
	v_fmac_f32_e32 v131, 0xba000000, v46
	v_fmac_f32_e32 v133, 0xba000000, v46
	v_mov_b32_e32 v160, v132
	v_mov_b32_e32 v161, v130
	v_add_f32_e32 v0, v2, v0
	v_add_f32_e32 v2, v6, v7
	v_pk_fma_f32 v[158:159], v[100:101], v[100:101], v[158:159]
	v_pk_mul_f32 v[160:161], v[160:161], v[160:161]
	v_mov_b32_e32 v164, v133
	v_mov_b32_e32 v165, v131
	v_fmac_f32_e32 v75, 0xba000000, v46
	v_fmac_f32_e32 v74, 0xba000000, v46
	v_add_f32_e32 v0, v2, v0
	v_add_f32_e32 v2, v8, v9
	v_pk_fma_f32 v[160:161], v[164:165], v[164:165], v[160:161]
	v_fmac_f32_e32 v69, 0xba000000, v46
	v_fmac_f32_e32 v68, 0xba000000, v46
	v_pk_mul_f32 v[164:165], v[74:75], v[74:75]
	v_fmac_f32_e32 v73, 0xba000000, v46
	v_fmac_f32_e32 v77, 0xba000000, v46
	v_fmac_f32_e32 v76, 0xba000000, v46
	v_add_f32_e32 v0, v2, v0
	v_add_f32_e32 v2, v158, v159
	v_pk_fma_f32 v[164:165], v[68:69], v[68:69], v[164:165]
	v_fmac_f32_e32 v71, 0xba000000, v46
	v_pk_mul_f32 v[174:175], v[76:77], v[76:77]
	v_mov_b32_e32 v70, v73
	v_add_f32_e32 v0, v2, v0
	v_add_f32_e32 v2, v160, v161
	v_pk_fma_f32 v[174:175], v[70:71], v[70:71], v[174:175]
	v_add_f32_e32 v0, v2, v0
	v_add_f32_e32 v2, v164, v165
	v_add_f32_e32 v0, v2, v0
	v_add_f32_e32 v2, v174, v175
	v_add_f32_e32 v0, v2, v0
	global_load_dwordx4 v[2:5], v[16:17], off
	global_load_dwordx4 v[6:9], v[18:19], off
	v_add_f32_dpp v0, v0, v0 quad_perm:[1,0,3,2] row_mask:0xf bank_mask:0xf bound_ctrl:1
	v_pk_mul_f32 v[10:11], v[10:11], v[116:117] op_sel_hi:[1,0]
	v_pk_mul_f32 v[12:13], v[12:13], v[116:117] op_sel_hi:[1,0]
	v_add_f32_dpp v0, v0, v0 quad_perm:[2,3,0,1] row_mask:0xf bank_mask:0xf bound_ctrl:1
	v_lshl_add_u64 v[174:175], s[54:55], 0, v[14:15]
	s_waitcnt vmcnt(0)
	v_pk_fma_f32 v[12:13], v[12:13], v[4:5], v[8:9]
	v_add_f32_dpp v0, v0, v0 row_half_mirror row_mask:0xf bank_mask:0xf bound_ctrl:1
	v_pk_fma_f32 v[10:11], v[10:11], v[2:3], v[6:7]
	global_store_dwordx4 v[174:175], v[10:13], off
	v_add_f32_dpp v0, v0, v0 row_ror:8 row_mask:0xf bank_mask:0xf bound_ctrl:1
	s_nop 0
	v_readlane_b32 s29, v0, 0
	v_readlane_b32 s39, v0, 16
	v_readlane_b32 s38, v0, 32
	v_readlane_b32 s44, v0, 48
	v_cndmask_b32_e64 v0, 0, 1, s[22:23]
	v_cmp_ne_u32_e64 s[2:3], 1, v0
	v_lshlrev_b32_e32 v0, 3, v138
	s_cbranch_vccnz .LBB0_157
	v_bfe_u32 v38, v10, 16, 1
	v_add3_u32 v10, v10, v38, s60
	v_bfe_u32 v38, v11, 16, 1
	v_lshrrev_b32_e32 v10, 16, v10
	v_add3_u32 v11, v11, v38, s60
	v_and_or_b32 v10, v11, s33, v10
	v_bfe_u32 v11, v12, 16, 1
	v_add3_u32 v11, v12, v11, s60
	v_bfe_u32 v12, v13, 16, 1
	v_lshrrev_b32_e32 v11, 16, v11
	v_add3_u32 v12, v13, v12, s60
	v_and_or_b32 v11, v12, s33, v11
	global_store_dwordx2 v0, v[10:11], s[66:67]

.LBB0_3254:
	global_load_dwordx4 v[140:143], v0, s[10:11]
	global_load_dwordx4 v[144:147], v0, s[10:11] offset:1024
	global_load_dwordx4 v[148:151], v0, s[10:11] offset:2048
	global_load_dwordx4 v[152:155], v0, s[10:11] offset:3072
	v_lshl_add_u64 v[8:9], s[10:11], 0, v[0:1]
	v_add_co_u32_e32 v8, vcc, s73, v8
	s_nop 1
	v_addc_co_u32_e32 v9, vcc, 0, v9, vcc
	global_load_dwordx4 v[156:159], v[8:9], off
	global_load_dwordx4 v[160:163], v[8:9], off offset:1024
	global_load_dwordx4 v[164:167], v[8:9], off offset:2048
	global_load_dwordx4 v[168:171], v[8:9], off offset:3072
	s_lshl_b64 s[0:1], s[8:9], 12
	s_add_u32 s8, s92, s0
	s_addc_u32 s9, s93, s1
	s_add_u32 s6, s6, s50
	s_addc_u32 s7, s7, s51
	s_add_u32 s2, s2, s74
	s_addc_u32 s3, s3, s75
	s_cmpk_gt_i32 s6, 0x21ff
	s_waitcnt vmcnt(7)
	v_bfe_u32 v172, v140, 16, 1
	v_bfe_u32 v173, v141, 16, 1
	v_bfe_u32 v174, v142, 16, 1
	v_bfe_u32 v175, v143, 16, 1
	v_add3_u32 v172, v140, v172, s60
	v_add3_u32 v173, v141, v173, s60
	v_add3_u32 v174, v142, v174, s60
	v_add3_u32 v175, v143, v175, s60
	v_lshrrev_b32_e32 v172, 16, v172
	v_lshrrev_b32_e32 v174, 16, v174
	v_and_or_b32 v140, v173, s33, v172
	v_and_or_b32 v141, v175, s33, v174
	global_store_dwordx2 v2, v[140:141], s[8:9]
	s_waitcnt vmcnt(7)
	v_bfe_u32 v172, v144, 16, 1
	v_bfe_u32 v173, v145, 16, 1
	v_bfe_u32 v174, v146, 16, 1
	v_bfe_u32 v175, v147, 16, 1
	v_add3_u32 v172, v144, v172, s60
	v_add3_u32 v173, v145, v173, s60
	v_add3_u32 v174, v146, v174, s60
	v_add3_u32 v175, v147, v175, s60
	v_lshrrev_b32_e32 v172, 16, v172
	v_lshrrev_b32_e32 v174, 16, v174
	v_and_or_b32 v144, v173, s33, v172
	v_and_or_b32 v145, v175, s33, v174
	global_store_dwordx2 v2, v[144:145], s[8:9] offset:512
	s_waitcnt vmcnt(7)
	v_bfe_u32 v172, v148, 16, 1
	v_bfe_u32 v173, v149, 16, 1
	v_bfe_u32 v174, v150, 16, 1
	v_bfe_u32 v175, v151, 16, 1
	v_add3_u32 v172, v148, v172, s60
	v_add3_u32 v173, v149, v173, s60
	v_add3_u32 v174, v150, v174, s60
	v_add3_u32 v175, v151, v175, s60
	v_lshrrev_b32_e32 v172, 16, v172
	v_lshrrev_b32_e32 v174, 16, v174
	v_and_or_b32 v148, v173, s33, v172
	v_and_or_b32 v149, v175, s33, v174
	global_store_dwordx2 v2, v[148:149], s[8:9] offset:1024
	s_waitcnt vmcnt(7)
	v_bfe_u32 v172, v152, 16, 1
	v_bfe_u32 v173, v153, 16, 1
	v_bfe_u32 v174, v154, 16, 1
	v_bfe_u32 v175, v155, 16, 1
	v_add3_u32 v172, v152, v172, s60
	v_add3_u32 v173, v153, v173, s60
	v_add3_u32 v174, v154, v174, s60
	v_add3_u32 v175, v155, v175, s60
	v_lshrrev_b32_e32 v172, 16, v172
	v_lshrrev_b32_e32 v174, 16, v174
	v_and_or_b32 v152, v173, s33, v172
	v_and_or_b32 v153, v175, s33, v174
	global_store_dwordx2 v2, v[152:153], s[8:9] offset:1536
	s_waitcnt vmcnt(7)
	v_bfe_u32 v172, v156, 16, 1
	v_bfe_u32 v173, v157, 16, 1
	v_bfe_u32 v174, v158, 16, 1
	v_bfe_u32 v175, v159, 16, 1
	v_add3_u32 v172, v156, v172, s60
	v_add3_u32 v173, v157, v173, s60
	v_add3_u32 v174, v158, v174, s60
	v_add3_u32 v175, v159, v175, s60
	v_lshrrev_b32_e32 v172, 16, v172
	v_lshrrev_b32_e32 v174, 16, v174
	v_and_or_b32 v156, v173, s33, v172
	v_and_or_b32 v157, v175, s33, v174
	global_store_dwordx2 v2, v[156:157], s[8:9] offset:2048
	s_waitcnt vmcnt(7)
	v_bfe_u32 v172, v160, 16, 1
	v_bfe_u32 v173, v161, 16, 1
	v_bfe_u32 v174, v162, 16, 1
	v_bfe_u32 v175, v163, 16, 1
	v_add3_u32 v172, v160, v172, s60
	v_add3_u32 v173, v161, v173, s60
	v_add3_u32 v174, v162, v174, s60
	v_add3_u32 v175, v163, v175, s60
	v_lshrrev_b32_e32 v172, 16, v172
	v_lshrrev_b32_e32 v174, 16, v174
	v_and_or_b32 v160, v173, s33, v172
	v_and_or_b32 v161, v175, s33, v174
	global_store_dwordx2 v2, v[160:161], s[8:9] offset:2560
	s_waitcnt vmcnt(7)
	v_bfe_u32 v172, v164, 16, 1
	v_bfe_u32 v173, v165, 16, 1
	v_bfe_u32 v174, v166, 16, 1
	v_bfe_u32 v175, v167, 16, 1
	v_add3_u32 v172, v164, v172, s60
	v_add3_u32 v173, v165, v173, s60
	v_add3_u32 v174, v166, v174, s60
	v_add3_u32 v175, v167, v175, s60
	v_lshrrev_b32_e32 v172, 16, v172
	v_lshrrev_b32_e32 v174, 16, v174
	v_and_or_b32 v164, v173, s33, v172
	v_and_or_b32 v165, v175, s33, v174
	global_store_dwordx2 v2, v[164:165], s[8:9] offset:3072
	s_waitcnt vmcnt(7)
	v_bfe_u32 v172, v168, 16, 1
	v_bfe_u32 v173, v169, 16, 1
	v_bfe_u32 v174, v170, 16, 1
	v_bfe_u32 v175, v171, 16, 1
	v_add3_u32 v172, v168, v172, s60
	v_add3_u32 v173, v169, v173, s60
	v_add3_u32 v174, v170, v174, s60
	v_add3_u32 v175, v171, v175, s60
	v_lshrrev_b32_e32 v172, 16, v172
	v_lshrrev_b32_e32 v174, 16, v174
	v_and_or_b32 v168, v173, s33, v172
	v_and_or_b32 v169, v175, s33, v174
	global_store_dwordx2 v2, v[168:169], s[8:9] offset:3584
	s_cbranch_scc1 .LBB0_3259

.LBB0_3261:
	s_mov_b32 s0, 1
	s_ashr_i32 s1, s0, 31
	s_lshl_b64 s[0:1], s[0:1], 3
	s_add_u32 s0, s48, s0
	s_addc_u32 s1, s49, s1
	s_load_dwordx2 s[0:1], s[0:1], 0x0
	s_add_i32 s18, s18, s50
	s_waitcnt lgkmcnt(0)
	v_lshl_add_u64 v[8:9], s[0:1], 0, v[2:3]
	global_load_dwordx4 v[140:143], v[8:9], off offset:-4096
	global_load_dwordx4 v[144:147], v[8:9], off offset:-3072
	global_load_dwordx4 v[148:151], v[8:9], off offset:-2048
	global_load_dwordx4 v[152:155], v[8:9], off offset:-1024
	global_load_dwordx4 v[156:159], v[8:9], off offset:0
	global_load_dwordx4 v[160:163], v[8:9], off offset:1024
	global_load_dwordx4 v[164:167], v[8:9], off offset:2048
	global_load_dwordx4 v[168:171], v[8:9], off offset:3072
	v_lshl_add_u64 v[2:3], v[2:3], 0, s[74:75]
	s_waitcnt vmcnt(7)
	v_bfe_u32 v172, v140, 16, 1
	v_bfe_u32 v173, v141, 16, 1
	v_bfe_u32 v174, v142, 16, 1
	v_bfe_u32 v175, v143, 16, 1
	v_add3_u32 v172, v140, v172, s60
	v_add3_u32 v173, v141, v173, s60
	v_add3_u32 v174, v142, v174, s60
	v_add3_u32 v175, v143, v175, s60
	v_lshrrev_b32_e32 v172, 16, v172
	v_lshrrev_b32_e32 v174, 16, v174
	v_and_or_b32 v140, v173, s33, v172
	v_and_or_b32 v141, v175, s33, v174
	global_store_dwordx2 v0, v[140:141], s[2:3]
	s_waitcnt vmcnt(7)
	v_bfe_u32 v172, v144, 16, 1
	v_bfe_u32 v173, v145, 16, 1
	v_bfe_u32 v174, v146, 16, 1
	v_bfe_u32 v175, v147, 16, 1
	v_add3_u32 v172, v144, v172, s60
	v_add3_u32 v173, v145, v173, s60
	v_add3_u32 v174, v146, v174, s60
	v_add3_u32 v175, v147, v175, s60
	v_lshrrev_b32_e32 v172, 16, v172
	v_lshrrev_b32_e32 v174, 16, v174
	v_and_or_b32 v144, v173, s33, v172
	v_and_or_b32 v145, v175, s33, v174
	global_store_dwordx2 v0, v[144:145], s[2:3] offset:512
	s_waitcnt vmcnt(7)
	v_bfe_u32 v172, v148, 16, 1
	v_bfe_u32 v173, v149, 16, 1
	v_bfe_u32 v174, v150, 16, 1
	v_bfe_u32 v175, v151, 16, 1
	v_add3_u32 v172, v148, v172, s60
	v_add3_u32 v173, v149, v173, s60
	v_add3_u32 v174, v150, v174, s60
	v_add3_u32 v175, v151, v175, s60
	v_lshrrev_b32_e32 v172, 16, v172
	v_lshrrev_b32_e32 v174, 16, v174
	v_and_or_b32 v148, v173, s33, v172
	v_and_or_b32 v149, v175, s33, v174
	global_store_dwordx2 v0, v[148:149], s[2:3] offset:1024
	s_waitcnt vmcnt(7)
	v_bfe_u32 v172, v152, 16, 1
	v_bfe_u32 v173, v153, 16, 1
	v_bfe_u32 v174, v154, 16, 1
	v_bfe_u32 v175, v155, 16, 1
	v_add3_u32 v172, v152, v172, s60
	v_add3_u32 v173, v153, v173, s60
	v_add3_u32 v174, v154, v174, s60
	v_add3_u32 v175, v155, v175, s60
	v_lshrrev_b32_e32 v172, 16, v172
	v_lshrrev_b32_e32 v174, 16, v174
	v_and_or_b32 v152, v173, s33, v172
	v_and_or_b32 v153, v175, s33, v174
	global_store_dwordx2 v0, v[152:153], s[2:3] offset:1536
	s_waitcnt vmcnt(7)
	v_bfe_u32 v172, v156, 16, 1
	v_bfe_u32 v173, v157, 16, 1
	v_bfe_u32 v174, v158, 16, 1
	v_bfe_u32 v175, v159, 16, 1
	v_add3_u32 v172, v156, v172, s60
	v_add3_u32 v173, v157, v173, s60
	v_add3_u32 v174, v158, v174, s60
	v_add3_u32 v175, v159, v175, s60
	v_lshrrev_b32_e32 v172, 16, v172
	v_lshrrev_b32_e32 v174, 16, v174
	v_and_or_b32 v156, v173, s33, v172
	v_and_or_b32 v157, v175, s33, v174
	global_store_dwordx2 v0, v[156:157], s[2:3] offset:2048
	s_waitcnt vmcnt(7)
	v_bfe_u32 v172, v160, 16, 1
	v_bfe_u32 v173, v161, 16, 1
	v_bfe_u32 v174, v162, 16, 1
	v_bfe_u32 v175, v163, 16, 1
	v_add3_u32 v172, v160, v172, s60
	v_add3_u32 v173, v161, v173, s60
	v_add3_u32 v174, v162, v174, s60
	v_add3_u32 v175, v163, v175, s60
	v_lshrrev_b32_e32 v172, 16, v172
	v_lshrrev_b32_e32 v174, 16, v174
	v_and_or_b32 v160, v173, s33, v172
	v_and_or_b32 v161, v175, s33, v174
	global_store_dwordx2 v0, v[160:161], s[2:3] offset:2560
	s_waitcnt vmcnt(7)
	v_bfe_u32 v172, v164, 16, 1
	v_bfe_u32 v173, v165, 16, 1
	v_bfe_u32 v174, v166, 16, 1
	v_bfe_u32 v175, v167, 16, 1
	v_add3_u32 v172, v164, v172, s60
	v_add3_u32 v173, v165, v173, s60
	v_add3_u32 v174, v166, v174, s60
	v_add3_u32 v175, v167, v175, s60
	v_lshrrev_b32_e32 v172, 16, v172
	v_lshrrev_b32_e32 v174, 16, v174
	v_and_or_b32 v164, v173, s33, v172
	v_and_or_b32 v165, v175, s33, v174
	global_store_dwordx2 v0, v[164:165], s[2:3] offset:3072
	s_waitcnt vmcnt(7)
	v_bfe_u32 v172, v168, 16, 1
	v_bfe_u32 v173, v169, 16, 1
	v_bfe_u32 v174, v170, 16, 1
	v_bfe_u32 v175, v171, 16, 1
	v_add3_u32 v172, v168, v172, s60
	v_add3_u32 v173, v169, v173, s60
	v_add3_u32 v174, v170, v174, s60
	v_add3_u32 v175, v171, v175, s60
	v_lshrrev_b32_e32 v172, 16, v172
	v_lshrrev_b32_e32 v174, 16, v174
	v_and_or_b32 v168, v173, s33, v172
	v_and_or_b32 v169, v175, s33, v174
	global_store_dwordx2 v0, v[168:169], s[2:3] offset:3584
	s_add_u32 s2, s2, s70
	s_addc_u32 s3, s3, s71
	s_cmpk_gt_i32 s18, 0x3ff
	s_cbranch_scc0 .LBB0_3261
	s_getpc_b64 s[98:99]
